# all 32 NA bias reads unconditional; MLA row-max canonicalisations and row-sum +0 heads removed
# speedup vs baseline: 1.0131x; 1.0072x over previous
; #define MFMA32(a, b, c) __builtin_amdgcn_mfma_f32_32x32x16_bf16(__builtin_bit_cast(bf16x8, (a)), __builtin_bit_cast(bf16x8, (b)), (c), 0, 0, 0)
; DI float ex2(float x) { return __builtin_amdgcn_exp2f(x); }
; DI int crow(int reg, int h) { return (reg & 3) + 8 * (reg >> 2) + 4 * h; }
; template <int DQK, bool NA>
; DI void attn_unit(const bf16_t* __restrict__ Qb, int ldq, const bf16_t* __restrict__ Kb, int ldk, const bf16_t* __restrict__ Vt,
;                   bf16_t* __restrict__ Ob, int ldo, int u, float sc, const float* __restrict__ rpb_h, char* smem) {
;     ...
;     if (active) {
;       const bf16_t* cK = sK + cur * 64 * KS + r * KS + 8 * h;
;       const bf16_t* cV = sV + cur * 64 * 72 + r * 72 + 8 * h;
;       f32x16 s0, s1;
;       {
;         const f32x16 zero16 = {0.f, 0.f, 0.f, 0.f, 0.f, 0.f, 0.f, 0.f, 0.f, 0.f, 0.f, 0.f, 0.f, 0.f, 0.f, 0.f};
;         u32x4 k0 = *(const u32x4*)(cK);
;         u32x4 k1 = *(const u32x4*)(cK + 32 * KS);
;         s0 = MFMA32(k0, qf[0], zero16);
;         s1 = MFMA32(k1, qf[0], zero16);
;       }
; #pragma unroll
;       for (int ds = 1; ds < NDS; ++ds) {
;         u32x4 k0 = *(const u32x4*)(cK + ds * 16);
;         u32x4 k1 = *(const u32x4*)(cK + 32 * KS + ds * 16);
;         s0 = MFMA32(k0, qf[ds], s0);
;         s1 = MFMA32(k1, qf[ds], s1);
;       }
;       if (NA) {
;         const int brow = (kt - rq + 7) * 31;
; #pragma unroll
;         for (int q = 0; q < 16; ++q) {
;           int kc0 = crow(q, h), kc1 = 32 + kc0;
;           bool v0 = (kc0 >= cs) && (kc0 < cs + 16), v1 = (kc1 >= cs) && (kc1 < cs + 16);
;           float b0 = v0 ? sBias[brow + kc0 - cq + 15] : 0.f;
;           float b1 = v1 ? sBias[brow + kc1 - cq + 15] : 0.f;
;           s0[q] = v0 ? (s0[q] * sc + b0) : -INFINITY;
;           s1[q] = v1 ? (s1[q] * sc + b1) : -INFINITY;
;         }
;       }
;       float mx = s0[0];
; #pragma unroll
;       for (int q = 1; q < 16; ++q) mx = fmaxf(mx, s0[q]);
; #pragma unroll
;       for (int q = 0; q < 16; ++q) mx = fmaxf(mx, s1[q]);
;       mx = fmaxf(mx, __shfl_xor(mx, 32));
;       if (__builtin_amdgcn_ballot_w64((mx - m_run) > 8.f) != 0ull) {
;         const float m_new = fmaxf(m_run, mx);
;         const float alpha = ex2(m_run - m_new);
;         m_run = m_new;
;         l_run *= alpha;
; #pragma unroll
;         for (int q = 0; q < 16; ++q) { o0[q] *= alpha; o1[q] *= alpha; }
;       }
.LBB0_296:
	v_cmp_ge_u32_e32 vcc, s97, v137
	v_cmp_lt_u32_e64 s[88:89], s97, v138
	s_and_b32 s1, s97, 1
	s_and_b64 vcc, vcc, s[88:89]
	s_and_saveexec_b64 s[88:89], vcc
	s_cbranch_execz .LBB0_360
	s_mul_i32 s4, s1, 0x2400
	v_add_u32_e32 v0, s4, v139
	ds_read_b128 v[2:5], v0
	ds_read_b128 v[6:9], v0 offset:4704
	s_waitcnt lgkmcnt(1)
	v_mfma_f32_32x32x16_bf16 v[64:79], v[2:5], v[80:83], 0
	ds_read_b128 v[2:5], v0 offset:4608
	s_waitcnt lgkmcnt(0)
	v_mfma_f32_32x32x16_bf16 v[48:63], v[2:5], v[80:83], 0
	ds_read_b128 v[2:5], v0 offset:32
	s_waitcnt lgkmcnt(0)
	v_mfma_f32_32x32x16_bf16 v[64:79], v[2:5], v[84:87], v[64:79]
	ds_read_b128 v[2:5], v0 offset:4640
	s_waitcnt lgkmcnt(0)
	v_mfma_f32_32x32x16_bf16 v[48:63], v[2:5], v[84:87], v[48:63]
	ds_read_b128 v[2:5], v0 offset:64
	s_waitcnt lgkmcnt(0)
	v_mfma_f32_32x32x16_bf16 v[64:79], v[2:5], v[88:91], v[64:79]
	ds_read_b128 v[2:5], v0 offset:4672
	s_waitcnt lgkmcnt(0)
	v_mfma_f32_32x32x16_bf16 v[48:63], v[2:5], v[88:91], v[48:63]
	ds_read_b128 v[2:5], v0 offset:96
	s_waitcnt lgkmcnt(0)
	v_mfma_f32_32x32x16_bf16 v[64:79], v[2:5], v[92:95], v[64:79]
	v_mfma_f32_32x32x16_bf16 v[48:63], v[6:9], v[92:95], v[48:63]
	ds_read_b32 v3, v141
	ds_read_b32 v117, v141 offset:128
	ds_read_b32 v5, v141 offset:4
	ds_read_b32 v142, v141 offset:132
	ds_read_b32 v143, v141 offset:8
	ds_read_b32 v144, v141 offset:136
	ds_read_b32 v145, v141 offset:12
	ds_read_b32 v146, v141 offset:140
	ds_read_b32 v147, v141 offset:32
	ds_read_b32 v148, v141 offset:160
	ds_read_b32 v149, v141 offset:36
	ds_read_b32 v150, v141 offset:164
	ds_read_b32 v151, v141 offset:40
	ds_read_b32 v152, v141 offset:168
	ds_read_b32 v153, v141 offset:44
	ds_read_b32 v154, v141 offset:172
	ds_read_b32 v14, v141 offset:64
	ds_read_b32 v155, v141 offset:192
	ds_read_b32 v15, v141 offset:68
	ds_read_b32 v156, v141 offset:196
	ds_read_b32 v10, v141 offset:72
	ds_read_b32 v12, v141 offset:200
	ds_read_b32 v11, v141 offset:76
	ds_read_b32 v13, v141 offset:204
	ds_read_b32 v6, v141 offset:96
	ds_read_b32 v8, v141 offset:224
	ds_read_b32 v7, v141 offset:100
	ds_read_b32 v9, v141 offset:228
	ds_read_b32 v2, v141 offset:104
	ds_read_b32 v4, v141 offset:232
	ds_read_b32 v157, v141 offset:108
	ds_read_b32 v158, v141 offset:236
	s_waitcnt lgkmcnt(0)
	v_fmac_f32_e32 v5, 0x3e38aa3b, v65
	v_fmac_f32_e32 v3, 0x3e38aa3b, v64
	v_fmac_f32_e32 v145, 0x3e38aa3b, v67
	v_fmac_f32_e32 v143, 0x3e38aa3b, v66
	v_cndmask_b32_e64 v65, v5, v129, s[10:11]
	v_cndmask_b32_e64 v64, v3, v129, s[6:7]
	v_fmac_f32_e32 v4, 0x3e38aa3b, v62
	v_fmac_f32_e32 v149, 0x3e38aa3b, v69
	v_fmac_f32_e32 v147, 0x3e38aa3b, v68
	v_cndmask_b32_e64 v67, v145, v129, s[22:23]
	v_cndmask_b32_e64 v66, v143, v129, s[16:17]
	v_max_f32_e32 v62, v64, v65
	v_fmac_f32_e32 v9, 0x3e38aa3b, v61
	v_fmac_f32_e32 v8, 0x3e38aa3b, v60
	v_fmac_f32_e32 v153, 0x3e38aa3b, v71
	v_fmac_f32_e32 v151, 0x3e38aa3b, v70
	v_cndmask_b32_e64 v61, v149, v129, s[36:37]
	v_cndmask_b32_e64 v60, v147, v129, s[28:29]
	v_max3_f32 v62, v62, v66, v67
	v_fmac_f32_e32 v13, 0x3e38aa3b, v59
	v_fmac_f32_e32 v12, 0x3e38aa3b, v58
	v_fmac_f32_e32 v15, 0x3e38aa3b, v73
	v_fmac_f32_e32 v14, 0x3e38aa3b, v72
	v_cndmask_b32_e64 v59, v153, v129, s[48:49]
	v_cndmask_b32_e64 v58, v151, v129, s[42:43]
	v_max3_f32 v62, v62, v60, v61
	v_fmac_f32_e32 v11, 0x3e38aa3b, v75
	v_fmac_f32_e32 v10, 0x3e38aa3b, v74
	v_cndmask_b32_e64 v15, v129, v15, s[58:59]
	v_cndmask_b32_e64 v14, v129, v14, s[54:55]
	v_max3_f32 v62, v62, v58, v59
	v_fmac_f32_e32 v7, 0x3e38aa3b, v77
	v_fmac_f32_e32 v6, 0x3e38aa3b, v76
	v_cndmask_b32_e64 v11, v129, v11, s[66:67]
	v_cndmask_b32_e64 v10, v129, v10, s[62:63]
	v_max3_f32 v62, v62, v14, v15
	v_fmac_f32_e32 v2, 0x3e38aa3b, v78
	v_cndmask_b32_e64 v7, v129, v7, s[74:75]
	v_cndmask_b32_e64 v6, v129, v6, s[70:71]
	v_fmac_f32_e32 v157, 0x3e38aa3b, v79
	v_max3_f32 v62, v62, v10, v11
	v_cndmask_b32_e64 v2, v129, v2, s[78:79]
	v_fmac_f32_e32 v142, 0x3e38aa3b, v49
	v_fmac_f32_e32 v117, 0x3e38aa3b, v48
	v_cndmask_b32_e64 v3, v129, v157, s[80:81]
	v_max3_f32 v62, v62, v6, v7
	v_fmac_f32_e32 v146, 0x3e38aa3b, v51
	v_fmac_f32_e32 v144, 0x3e38aa3b, v50
	v_cndmask_b32_e64 v49, v129, v142, s[14:15]
	v_cndmask_b32_e64 v48, v129, v117, s[8:9]
	v_max3_f32 v62, v62, v2, v3
	v_fmac_f32_e32 v150, 0x3e38aa3b, v53
	v_fmac_f32_e32 v148, 0x3e38aa3b, v52
	v_cndmask_b32_e64 v51, v129, v146, s[26:27]
	v_cndmask_b32_e64 v50, v129, v144, s[20:21]
	v_max3_f32 v62, v62, v48, v49
	v_fmac_f32_e32 v154, 0x3e38aa3b, v55
	v_fmac_f32_e32 v152, 0x3e38aa3b, v54
	v_cndmask_b32_e64 v53, v129, v150, s[40:41]
	v_cndmask_b32_e64 v52, v129, v148, s[34:35]
	v_max3_f32 v62, v62, v50, v51
	v_fmac_f32_e32 v156, 0x3e38aa3b, v57
	v_fmac_f32_e32 v155, 0x3e38aa3b, v56
	v_cndmask_b32_e64 v55, v129, v154, s[52:53]
	v_cndmask_b32_e64 v54, v129, v152, s[46:47]
	v_max3_f32 v62, v62, v52, v53
	v_cndmask_b32_e64 v57, v129, v156, s[60:61]
	v_cndmask_b32_e64 v56, v129, v155, s[56:57]
	v_max3_f32 v62, v62, v54, v55
	v_and_b32_e32 v68, 64, v197
	v_cndmask_b32_e64 v13, v129, v13, s[68:69]
	v_cndmask_b32_e64 v12, v129, v12, s[64:65]
	v_fmac_f32_e32 v158, 0x3e38aa3b, v63
	v_max3_f32 v62, v62, v56, v57
	v_xor_b32_e32 v63, 32, v197
	v_add_u32_e32 v68, 64, v68
	v_cndmask_b32_e64 v9, v129, v9, s[76:77]
	v_cndmask_b32_e64 v8, v129, v8, s[72:73]
	v_max3_f32 v62, v62, v12, v13
	v_cmp_lt_i32_e32 vcc, v63, v68
	v_cndmask_b32_e64 v4, v129, v4, s[82:83]
	v_cndmask_b32_e64 v5, v129, v158, s[84:85]
	v_max3_f32 v62, v62, v8, v9
	v_cndmask_b32_e32 v63, v197, v63, vcc
	v_max3_f32 v62, v62, v4, v5
	v_lshlrev_b32_e32 v63, 2, v63
	ds_bpermute_b32 v63, v63, v62
	s_waitcnt lgkmcnt(0)
	v_max_f32_e32 v63, v63, v63
	v_max_f32_e32 v62, v62, v63
	v_sub_f32_e32 v63, v62, v124
	v_cmp_lt_f32_e32 vcc, s0, v63
	s_cbranch_vccz .LBB0_359
	v_max_f32_e32 v62, v62, v62
	v_max_f32_e32 v63, v124, v124
	v_max_f32_e32 v63, v63, v62
	v_sub_f32_e32 v62, v124, v63
	v_exp_f32_e32 v62, v62
	v_mov_b32_e32 v124, v63
	v_pk_mul_f32 v[46:47], v[46:47], v[62:63] op_sel_hi:[1,0]
	v_pk_mul_f32 v[44:45], v[44:45], v[62:63] op_sel_hi:[1,0]
	v_pk_mul_f32 v[42:43], v[42:43], v[62:63] op_sel_hi:[1,0]
	v_pk_mul_f32 v[40:41], v[40:41], v[62:63] op_sel_hi:[1,0]
	v_pk_mul_f32 v[38:39], v[38:39], v[62:63] op_sel_hi:[1,0]
	v_pk_mul_f32 v[36:37], v[36:37], v[62:63] op_sel_hi:[1,0]
	v_pk_mul_f32 v[34:35], v[34:35], v[62:63] op_sel_hi:[1,0]
	v_pk_mul_f32 v[32:33], v[32:33], v[62:63] op_sel_hi:[1,0]
	v_pk_mul_f32 v[30:31], v[30:31], v[62:63] op_sel_hi:[1,0]
	v_pk_mul_f32 v[28:29], v[28:29], v[62:63] op_sel_hi:[1,0]
	v_pk_mul_f32 v[26:27], v[26:27], v[62:63] op_sel_hi:[1,0]
	v_pk_mul_f32 v[24:25], v[24:25], v[62:63] op_sel_hi:[1,0]
	v_pk_mul_f32 v[22:23], v[22:23], v[62:63] op_sel_hi:[1,0]
	v_pk_mul_f32 v[20:21], v[20:21], v[62:63] op_sel_hi:[1,0]
	v_pk_mul_f32 v[18:19], v[18:19], v[62:63] op_sel_hi:[1,0]
	v_pk_mul_f32 v[16:17], v[16:17], v[62:63] op_sel_hi:[1,0]
	v_mul_f32_e32 v140, v140, v62
; #define MFMA32(a, b, c) __builtin_amdgcn_mfma_f32_32x32x16_bf16(__builtin_bit_cast(bf16x8, (a)), __builtin_bit_cast(bf16x8, (b)), (c), 0, 0, 0)
; DI unsigned pack2(float a, float b) { f2_t f = {a, b}; bf2_t r = __builtin_convertvector(f, bf2_t); return __builtin_bit_cast(unsigned, r); }
; DI float ex2(float x) { return __builtin_amdgcn_exp2f(x); }
; template <int DQK, bool NA>
; DI void attn_unit(const bf16_t* __restrict__ Qb, int ldq, const bf16_t* __restrict__ Kb, int ldk, const bf16_t* __restrict__ Vt,
;                   bf16_t* __restrict__ Ob, int ldo, int u, float sc, const float* __restrict__ rpb_h, char* smem) {
;     ...
;       const f2_t nm = {-m_run, -m_run};
;       f2_t ls2 = {0.f, 0.f};
; #pragma unroll
;       for (int q = 0; q < 16; q += 2) {
;         f2_t a = {s0[q], s0[q + 1]}, b = {s1[q], s1[q + 1]};
;         a = a + nm; b = b + nm;
;         a[0] = ex2(a[0]); a[1] = ex2(a[1]); b[0] = ex2(b[0]); b[1] = ex2(b[1]);
;         s0[q] = a[0]; s0[q + 1] = a[1]; s1[q] = b[0]; s1[q + 1] = b[1];
;         ls2 = ls2 + a; ls2 = ls2 + b;
;       }
;       l_run += ls2[0] + ls2[1];
;       u32x4 pf[4];
; #pragma unroll
;       for (int s = 0; s < 2; ++s) {
;         pf[s][0] = pack2(s0[8 * s], s0[8 * s + 1]); pf[s][1] = pack2(s0[8 * s + 2], s0[8 * s + 3]);
;         pf[s][2] = pack2(s0[8 * s + 4], s0[8 * s + 5]); pf[s][3] = pack2(s0[8 * s + 6], s0[8 * s + 7]);
;         pf[2 + s][0] = pack2(s1[8 * s], s1[8 * s + 1]); pf[2 + s][1] = pack2(s1[8 * s + 2], s1[8 * s + 3]);
;         pf[2 + s][2] = pack2(s1[8 * s + 4], s1[8 * s + 5]); pf[2 + s][3] = pack2(s1[8 * s + 6], s1[8 * s + 7]);
;       }
; #pragma unroll
;       for (int ks = 0; ks < 4; ++ks) {
;         u32x4 v0 = *(const u32x4*)(cV + ks * 16);
;         u32x4 v1 = *(const u32x4*)(cV + 32 * 72 + ks * 16);
;         o0 = MFMA32(v0, pf[ks], o0);
;         o1 = MFMA32(v1, pf[ks], o1);
;       }
;     }
;     if (more) store_tile(cur ^ 1);
.LBB0_359:
	v_pk_add_f32 v[62:63], v[64:65], v[124:125] op_sel_hi:[1,0] neg_lo:[0,1] neg_hi:[0,1]
	v_pk_add_f32 v[48:49], v[48:49], v[124:125] op_sel_hi:[1,0] neg_lo:[0,1] neg_hi:[0,1]
	v_exp_f32_e32 v62, v62
	v_exp_f32_e32 v63, v63
	v_exp_f32_e32 v64, v48
	v_exp_f32_e32 v65, v49
	v_pk_add_f32 v[66:67], v[66:67], v[124:125] op_sel_hi:[1,0] neg_lo:[0,1] neg_hi:[0,1]
	v_pk_add_f32 v[50:51], v[50:51], v[124:125] op_sel_hi:[1,0] neg_lo:[0,1] neg_hi:[0,1]
	v_exp_f32_e32 v66, v66
	v_exp_f32_e32 v67, v67
	v_exp_f32_e32 v68, v50
	v_exp_f32_e32 v69, v51
	v_pk_add_f32 v[50:51], v[60:61], v[124:125] op_sel_hi:[1,0] neg_lo:[0,1] neg_hi:[0,1]
	v_pk_add_f32 v[52:53], v[52:53], v[124:125] op_sel_hi:[1,0] neg_lo:[0,1] neg_hi:[0,1]
	v_exp_f32_e32 v50, v50
	v_exp_f32_e32 v51, v51
	v_pk_add_f32 v[48:49], v[64:65], v[62:63]
	v_exp_f32_e32 v52, v52
	v_exp_f32_e32 v53, v53
	v_pk_add_f32 v[58:59], v[58:59], v[124:125] op_sel_hi:[1,0] neg_lo:[0,1] neg_hi:[0,1]
	v_pk_add_f32 v[48:49], v[66:67], v[48:49]
	v_pk_add_f32 v[54:55], v[54:55], v[124:125] op_sel_hi:[1,0] neg_lo:[0,1] neg_hi:[0,1]
	v_exp_f32_e32 v58, v58
	v_exp_f32_e32 v59, v59
	v_pk_add_f32 v[48:49], v[68:69], v[48:49]
	v_exp_f32_e32 v54, v54
	v_exp_f32_e32 v55, v55
	v_pk_add_f32 v[14:15], v[14:15], v[124:125] op_sel_hi:[1,0] neg_lo:[0,1] neg_hi:[0,1]
	v_pk_add_f32 v[48:49], v[50:51], v[48:49]
	v_pk_add_f32 v[56:57], v[56:57], v[124:125] op_sel_hi:[1,0] neg_lo:[0,1] neg_hi:[0,1]
	v_exp_f32_e32 v14, v14
	v_exp_f32_e32 v15, v15
	v_pk_add_f32 v[48:49], v[52:53], v[48:49]
	v_exp_f32_e32 v56, v56
	v_exp_f32_e32 v57, v57
	v_pk_add_f32 v[10:11], v[10:11], v[124:125] op_sel_hi:[1,0] neg_lo:[0,1] neg_hi:[0,1]
	v_pk_add_f32 v[48:49], v[58:59], v[48:49]
	v_pk_add_f32 v[12:13], v[12:13], v[124:125] op_sel_hi:[1,0] neg_lo:[0,1] neg_hi:[0,1]
	v_exp_f32_e32 v60, v10
	v_exp_f32_e32 v61, v11
	v_pk_add_f32 v[48:49], v[54:55], v[48:49]
	v_exp_f32_e32 v70, v12
	v_exp_f32_e32 v71, v13
	v_pk_add_f32 v[6:7], v[6:7], v[124:125] op_sel_hi:[1,0] neg_lo:[0,1] neg_hi:[0,1]
	v_pk_add_f32 v[48:49], v[14:15], v[48:49]
	v_pk_add_f32 v[8:9], v[8:9], v[124:125] op_sel_hi:[1,0] neg_lo:[0,1] neg_hi:[0,1]
	v_exp_f32_e32 v12, v6
	v_exp_f32_e32 v13, v7
	v_pk_add_f32 v[48:49], v[56:57], v[48:49]
	v_exp_f32_e32 v72, v8
	v_exp_f32_e32 v73, v9
	v_pk_add_f32 v[2:3], v[2:3], v[124:125] op_sel_hi:[1,0] neg_lo:[0,1] neg_hi:[0,1]
	v_pk_add_f32 v[10:11], v[60:61], v[48:49]
	v_exp_f32_e32 v2, v2
	v_exp_f32_e32 v3, v3
	v_pk_add_f32 v[10:11], v[70:71], v[10:11]
	v_pk_add_f32 v[4:5], v[4:5], v[124:125] op_sel_hi:[1,0] neg_lo:[0,1] neg_hi:[0,1]
	v_pk_add_f32 v[6:7], v[12:13], v[10:11]
	v_exp_f32_e32 v74, v4
	v_pk_add_f32 v[6:7], v[72:73], v[6:7]
	v_exp_f32_e32 v75, v5
	v_pk_add_f32 v[4:5], v[2:3], v[6:7]
	v_cvt_pk_bf16_f32 v48, v62, v63
	v_cvt_pk_bf16_f32 v50, v50, v51
	v_cvt_pk_bf16_f32 v51, v58, v59
	v_cvt_pk_bf16_f32 v8, v52, v53
	v_cvt_pk_bf16_f32 v9, v54, v55
	v_cvt_pk_bf16_f32 v11, v60, v61
	v_cvt_pk_bf16_f32 v12, v12, v13
	v_cvt_pk_bf16_f32 v13, v2, v3
	v_cvt_pk_bf16_f32 v2, v56, v57
	ds_read_b128 v[52:55], v0 offset:23040
	ds_read_b128 v[56:59], v0 offset:18432
	ds_read_b128 v[60:63], v0 offset:18464
	v_cvt_pk_bf16_f32 v49, v66, v67
	v_cvt_pk_bf16_f32 v10, v14, v15
	v_cvt_pk_bf16_f32 v6, v64, v65
	s_waitcnt lgkmcnt(1)
	v_mfma_f32_32x32x16_bf16 v[32:47], v[56:59], v[48:51], v[32:47]
	v_cvt_pk_bf16_f32 v7, v68, v69
	v_add_f32_e64 v4, v74, v4
	v_add_f32_e64 v5, v75, v5
	v_cvt_pk_bf16_f32 v3, v70, v71
	v_add_f32_e32 v76, v4, v5
	v_cvt_pk_bf16_f32 v4, v72, v73
	v_cvt_pk_bf16_f32 v5, v74, v75
	v_add_f32_e32 v140, v140, v76
	v_mfma_f32_32x32x16_bf16 v[16:31], v[52:55], v[48:51], v[16:31]
	ds_read_b128 v[48:51], v0 offset:23072
	s_waitcnt lgkmcnt(1)
	v_mfma_f32_32x32x16_bf16 v[32:47], v[60:63], v[10:13], v[32:47]
	s_waitcnt lgkmcnt(0)
	v_mfma_f32_32x32x16_bf16 v[16:31], v[48:51], v[10:13], v[16:31]
	ds_read_b128 v[10:13], v0 offset:18496
	ds_read_b128 v[48:51], v0 offset:23104
	s_waitcnt lgkmcnt(1)
	v_mfma_f32_32x32x16_bf16 v[32:47], v[10:13], v[6:9], v[32:47]
	s_waitcnt lgkmcnt(0)
	v_mfma_f32_32x32x16_bf16 v[16:31], v[48:51], v[6:9], v[16:31]
	ds_read_b128 v[6:9], v0 offset:18528
	ds_read_b128 v[10:13], v0 offset:23136
	s_waitcnt lgkmcnt(1)
	v_mfma_f32_32x32x16_bf16 v[32:47], v[6:9], v[2:5], v[32:47]
	s_waitcnt lgkmcnt(0)
	v_mfma_f32_32x32x16_bf16 v[16:31], v[10:13], v[2:5], v[16:31]
.LBB0_360:
	s_or_b64 exec, exec, s[88:89]
	s_andn2_b64 vcc, exec, s[90:91]
	s_cbranch_vccnz .LBB0_291
	s_xor_b32 s1, s1, 1
	s_mulk_i32 s1, 0x1200
	s_lshl_b32 s90, s1, 1
	v_lshlrev_b32_e32 v0, 1, v111
	v_add3_u32 v0, s90, v0, v113
	s_waitcnt vmcnt(1)
	ds_write_b128 v0, v[96:99]
	s_and_saveexec_b64 s[88:89], s[86:87]
	s_cbranch_execz .LBB0_290
	v_lshlrev_b32_e32 v0, 1, v116
	v_add3_u32 v0, s90, v115, v0
	ds_write_b128 v0, v[100:103]
	s_branch .LBB0_290
.LBB0_367:
	v_readlane_b32 s72, v247, 54
	v_readlane_b32 s38, v246, 36
	v_readlane_b32 s24, v246, 39
	v_readlane_b32 s36, v246, 43
	v_readlane_b32 s44, v246, 45
	s_mov_b64 s[4:5], 0
	v_readlane_b32 s74, v246, 35
	v_readlane_b32 s73, v247, 55
	v_readlane_b32 s39, v246, 37
	v_readlane_b32 s56, v247, 56
	v_readlane_b32 s40, v246, 38
	v_readlane_b32 s25, v246, 40
	v_readlane_b32 s26, v246, 41
	v_readlane_b32 s27, v246, 42
	s_movk_i32 s88, 0xf40
	s_movk_i32 s28, 0x90
	s_movk_i32 s29, 0xc0
	s_movk_i32 s30, 0x600
	s_mov_b32 s31, 0x2aaaaaab
	s_movk_i32 s34, 0x68
	v_readlane_b32 s37, v246, 44
	v_readlane_b32 s35, v246, 50
	v_readlane_b32 s41, v246, 49
	v_readlane_b32 s42, v246, 48
	v_readlane_b32 s43, v246, 47
	v_readlane_b32 s45, v246, 46

; DI float ex2(float x) { return __builtin_amdgcn_exp2f(x); }
; template <int DQK, bool NA>
; DI void attn_unit(const bf16_t* __restrict__ Qb, int ldq, const bf16_t* __restrict__ Kb, int ldk, const bf16_t* __restrict__ Vt,
;                   bf16_t* __restrict__ Ob, int ldo, int u, float sc, const float* __restrict__ rpb_h, char* smem) {
;     ...
;       const f2_t nm = {-m_run, -m_run};
;       f2_t ls2 = {0.f, 0.f};
; #pragma unroll
;       for (int q = 0; q < 16; q += 2) {
;         f2_t a = {s0[q], s0[q + 1]}, b = {s1[q], s1[q + 1]};
;         a = a + nm; b = b + nm;
;         a[0] = ex2(a[0]); a[1] = ex2(a[1]); b[0] = ex2(b[0]); b[1] = ex2(b[1]);
;         s0[q] = a[0]; s0[q + 1] = a[1]; s1[q] = b[0]; s1[q + 1] = b[1];
;         ls2 = ls2 + a; ls2 = ls2 + b;
;       }
;       l_run += ls2[0] + ls2[1];
;     ...
;     if (more) store_tile(cur ^ 1);
;     __syncthreads();
.LBB0_379:
	s_or_b64 exec, exec, s[2:3]
	s_mulk_i32 s6, 0x2400
	v_pk_add_f32 v[2:3], v[12:13], v[10:11]
	s_add_i32 s1, s1, 1
	v_pk_add_f32 v[2:3], v[14:15], v[2:3]
	s_mov_b64 s[2:3], 0x80
	v_pk_add_f32 v[2:3], v[48:49], v[2:3]
	v_lshl_add_u64 v[116:117], v[116:117], 0, s[2:3]
	v_pk_add_f32 v[2:3], v[50:51], v[2:3]
	v_lshl_add_u64 v[118:119], v[118:119], 0, s[94:95]
	v_pk_add_f32 v[2:3], v[72:73], v[2:3]
	s_cmp_eq_u32 s1, 63
	v_pk_add_f32 v[2:3], v[52:53], v[2:3]
	v_lshl_add_u64 v[122:123], v[122:123], 0, s[94:95]
	v_pk_add_f32 v[2:3], v[54:55], v[2:3]
	s_nop 0
	v_pk_add_f32 v[2:3], v[64:65], v[2:3]
	s_nop 0
	v_pk_add_f32 v[2:3], v[56:57], v[2:3]
	s_nop 0
	v_pk_add_f32 v[2:3], v[66:67], v[2:3]
	s_nop 0
	v_pk_add_f32 v[2:3], v[58:59], v[2:3]
	s_nop 0
	v_pk_add_f32 v[2:3], v[68:69], v[2:3]
	s_nop 0
	v_pk_add_f32 v[2:3], v[60:61], v[2:3]
	s_nop 0
	v_pk_add_f32 v[2:3], v[70:71], v[2:3]
	s_nop 0
	v_pk_add_f32 v[2:3], v[62:63], v[2:3]
	s_nop 0
	v_add_f32_e32 v0, v2, v3
	v_add_f32_e32 v115, v115, v0
	v_add_u32_e32 v0, s6, v136
	v_lshl_add_u32 v2, v137, 1, v0
	v_lshl_add_u32 v0, v138, 1, v0
	s_waitcnt vmcnt(0)
	ds_write_b64 v2, v[6:7] offset:26624
	ds_write_b64 v0, v[8:9] offset:26624
	s_waitcnt lgkmcnt(0)
	s_barrier
	s_cbranch_scc1 .LBB0_386

; #define MFMA32(a, b, c) __builtin_amdgcn_mfma_f32_32x32x16_bf16(__builtin_bit_cast(bf16x8, (a)), __builtin_bit_cast(bf16x8, (b)), (c), 0, 0, 0)
; DI float ex2(float x) { return __builtin_amdgcn_exp2f(x); }
; DI int crow(int reg, int h) { return (reg & 3) + 8 * (reg >> 2) + 4 * h; }
; template <int DQK, bool NA>
; DI void attn_unit(const bf16_t* __restrict__ Qb, int ldq, const bf16_t* __restrict__ Kb, int ldk, const bf16_t* __restrict__ Vt,
;                   bf16_t* __restrict__ Ob, int ldo, int u, float sc, const float* __restrict__ rpb_h, char* smem) {
;     ...
;       {
;         const f32x16 zero16 = {0.f, 0.f, 0.f, 0.f, 0.f, 0.f, 0.f, 0.f, 0.f, 0.f, 0.f, 0.f, 0.f, 0.f, 0.f, 0.f};
;         u32x4 k0 = *(const u32x4*)(cK);
;         u32x4 k1 = *(const u32x4*)(cK + 32 * KS);
;         s0 = MFMA32(k0, qf[0], zero16);
;         s1 = MFMA32(k1, qf[0], zero16);
;       }
; #pragma unroll
;       for (int ds = 1; ds < NDS; ++ds) {
;         u32x4 k0 = *(const u32x4*)(cK + ds * 16);
;         u32x4 k1 = *(const u32x4*)(cK + 32 * KS + ds * 16);
;         s0 = MFMA32(k0, qf[ds], s0);
;         s1 = MFMA32(k1, qf[ds], s1);
;       }
;       if (NA) {
;         const int brow = (kt - rq + 7) * 31;
; #pragma unroll
;         for (int q = 0; q < 16; ++q) {
;           int kc0 = crow(q, h), kc1 = 32 + kc0;
;           bool v0 = (kc0 >= cs) && (kc0 < cs + 16), v1 = (kc1 >= cs) && (kc1 < cs + 16);
;           float b0 = v0 ? sBias[brow + kc0 - cq + 15] : 0.f;
;           float b1 = v1 ? sBias[brow + kc1 - cq + 15] : 0.f;
;           s0[q] = v0 ? (s0[q] * sc + b0) : -INFINITY;
;           s1[q] = v1 ? (s1[q] * sc + b1) : -INFINITY;
;         }
;       }
;       float mx = s0[0];
; #pragma unroll
;       for (int q = 1; q < 16; ++q) mx = fmaxf(mx, s0[q]);
; #pragma unroll
;       for (int q = 0; q < 16; ++q) mx = fmaxf(mx, s1[q]);
;       mx = fmaxf(mx, __shfl_xor(mx, 32));
;       if (__builtin_amdgcn_ballot_w64((mx - m_run) > 8.f) != 0ull) {
;         const float m_new = fmaxf(m_run, mx);
;         const float alpha = ex2(m_run - m_new);
;         m_run = m_new;
;         l_run *= alpha;
; #pragma unroll
;         for (int q = 0; q < 16; ++q) { o0[q] *= alpha; o1[q] *= alpha; }
;       }
.LBB0_382:
	s_or_b64 exec, exec, s[2:3]
	s_and_b32 s2, s1, 1
	s_mul_i32 s3, s2, 0x3400
	v_add_u32_e32 v0, s3, v135
	ds_read_b128 v[6:9], v0
	ds_read_b128 v[10:13], v0 offset:32
	s_waitcnt lgkmcnt(1)
	v_mfma_f32_32x32x16_bf16 v[64:79], v[6:9], v[100:103], 0
	ds_read_b128 v[6:9], v0 offset:6656
	ds_read_b128 v[140:143], v0 offset:6688
	s_waitcnt lgkmcnt(2)
	v_mfma_f32_32x32x16_bf16 v[64:79], v[10:13], v[96:99], v[64:79]
	s_waitcnt lgkmcnt(1)
	v_mfma_f32_32x32x16_bf16 v[48:63], v[6:9], v[100:103], 0
	ds_read_b128 v[6:9], v0 offset:64
	ds_read_b128 v[10:13], v0 offset:96
	s_waitcnt lgkmcnt(1)
	v_mfma_f32_32x32x16_bf16 v[64:79], v[6:9], v[92:95], v[64:79]
	s_waitcnt lgkmcnt(0)
	v_mfma_f32_32x32x16_bf16 v[64:79], v[10:13], v[88:91], v[64:79]
	ds_read_b128 v[6:9], v0 offset:128
	ds_read_b128 v[10:13], v0 offset:160
	s_waitcnt lgkmcnt(1)
	v_mfma_f32_32x32x16_bf16 v[64:79], v[6:9], v[84:87], v[64:79]
	v_mfma_f32_32x32x16_bf16 v[48:63], v[140:143], v[96:99], v[48:63]
	s_waitcnt lgkmcnt(0)
	v_mfma_f32_32x32x16_bf16 v[64:79], v[10:13], v[80:83], v[64:79]
	ds_read_b128 v[6:9], v0 offset:6720
	ds_read_b128 v[10:13], v0 offset:6752
	s_waitcnt lgkmcnt(1)
	v_mfma_f32_32x32x16_bf16 v[48:63], v[6:9], v[92:95], v[48:63]
	global_load_dwordx4 v[6:9], v[116:117], off
	s_nop 6
	s_waitcnt lgkmcnt(0)
	v_mfma_f32_32x32x16_bf16 v[48:63], v[10:13], v[88:91], v[48:63]
	ds_read_b128 v[10:13], v0 offset:6784
	ds_read_b128 v[140:143], v0 offset:6816
	v_max_f32_e32 v0, v64, v65
	v_max3_f32 v0, v0, v66, v67
	v_max3_f32 v0, v0, v68, v69
	v_max3_f32 v0, v0, v70, v71
	v_max3_f32 v0, v0, v72, v73
	s_waitcnt lgkmcnt(1)
	v_mfma_f32_32x32x16_bf16 v[48:63], v[10:13], v[84:87], v[48:63]
	v_max3_f32 v0, v0, v74, v75
	v_max3_f32 v0, v0, v76, v77
	v_max3_f32 v0, v0, v78, v79
	s_waitcnt lgkmcnt(0)
	v_mfma_f32_32x32x16_bf16 v[48:63], v[140:143], v[80:83], v[48:63]
	s_nop 11
	v_max3_f32 v0, v0, v48, v49
	v_max3_f32 v0, v0, v50, v51
	v_max3_f32 v0, v0, v52, v53
	v_max3_f32 v0, v0, v54, v55
	v_max3_f32 v0, v0, v56, v57
	v_max3_f32 v0, v0, v58, v59
	v_max3_f32 v0, v0, v60, v61
	v_max3_f32 v0, v0, v62, v63
	ds_bpermute_b32 v10, v111, v0
	s_waitcnt lgkmcnt(0)
	v_max_f32_e32 v0, v0, v10
	v_sub_f32_e32 v10, v0, v120
	v_cmp_lt_f32_e32 vcc, s0, v10
	s_cbranch_vccz .LBB0_384
	v_max_f32_e32 v0, v0, v0
	v_max_f32_e32 v10, v120, v120
	v_max_f32_e32 v10, v10, v0
	v_sub_f32_e32 v0, v120, v10
	v_exp_f32_e32 v0, v0
	v_mov_b32_e32 v120, v10
	v_pk_mul_f32 v[46:47], v[46:47], v[0:1] op_sel_hi:[1,0]
	v_pk_mul_f32 v[44:45], v[44:45], v[0:1] op_sel_hi:[1,0]
	v_pk_mul_f32 v[42:43], v[42:43], v[0:1] op_sel_hi:[1,0]
	v_pk_mul_f32 v[40:41], v[40:41], v[0:1] op_sel_hi:[1,0]
	v_pk_mul_f32 v[38:39], v[38:39], v[0:1] op_sel_hi:[1,0]
	v_pk_mul_f32 v[36:37], v[36:37], v[0:1] op_sel_hi:[1,0]
	v_pk_mul_f32 v[34:35], v[34:35], v[0:1] op_sel_hi:[1,0]
	v_pk_mul_f32 v[32:33], v[32:33], v[0:1] op_sel_hi:[1,0]
	v_pk_mul_f32 v[30:31], v[30:31], v[0:1] op_sel_hi:[1,0]
	v_pk_mul_f32 v[28:29], v[28:29], v[0:1] op_sel_hi:[1,0]
	v_pk_mul_f32 v[26:27], v[26:27], v[0:1] op_sel_hi:[1,0]
	v_pk_mul_f32 v[24:25], v[24:25], v[0:1] op_sel_hi:[1,0]
	v_pk_mul_f32 v[22:23], v[22:23], v[0:1] op_sel_hi:[1,0]
	v_pk_mul_f32 v[20:21], v[20:21], v[0:1] op_sel_hi:[1,0]
	v_pk_mul_f32 v[18:19], v[18:19], v[0:1] op_sel_hi:[1,0]
	v_pk_mul_f32 v[16:17], v[16:17], v[0:1] op_sel_hi:[1,0]
	v_mul_f32_e32 v115, v115, v0
